# fast path v3: even/odd tile copies with immediate LDS offsets (no per-tile LDS address VALU); rest as v25
# baseline (speedup 1.0000x reference)
; #define LAS __attribute__((address_space(3)))
; __device__ __forceinline__ void phase_attn(const Params& p, int S, int lgS, int B, int* counter, LAS unsigned char* lds) {
;     ...
;     LAS float* wsf = (LAS float*)(lds + 2 * BUFB + wid * 256);
;     const int skey = tid >> 3, spc = tid & 7;
;     const int kdst = (skey * 72 + spc * 8) * 2, vdst = KB + (skey * 136 + spc * 8) * 2;
;     const int klane = (r32 * 72 + 8 * hi) * 2, vlane = (r32 * 136 + 4 * hi) * 2;
.LBB0_725:
	s_cmp_lt_i32 s1, 1
	s_cbranch_scc1 .LBB0_741
	s_ashr_i32 s4, s2, 6
	s_add_u32 s8, s6, 0x13800000
	s_addc_u32 s9, s7, 0
	s_lshl_b32 s2, s4, 8
	s_add_i32 s2, s2, 0
	v_lshlrev_b32_e32 v2, 3, v0
	v_bfe_u32 v3, v0, 5, 1
	s_add_i32 s10, s2, 0x11800
	v_ashrrev_i32_e32 v146, 3, v0
	v_and_b32_e32 v2, 56, v2
	s_movk_i32 s2, 0x48
	v_mad_u64_u32 v[4:5], s[2:3], v146, s2, v[2:3]
	v_readlane_b32 s2, v251, 30
	v_readlane_b32 s3, v251, 31
	v_and_b32_e32 v144, 31, v0
	v_lshlrev_b32_e32 v5, 6, v146
	v_readlane_b32 s3, v251, 39
	v_lshlrev_b32_e32 v145, 1, v4
	v_lshlrev_b32_e32 v149, 4, v0
	v_and_b32_e32 v149, 0x60, v149
	v_lshlrev_b32_e32 v5, 3, v0
	v_and_b32_e32 v5, 8, v5
	v_add_u32_e32 v149, v149, v5
	v_mul_u32_u24_e32 v5, 0x110, v146
	v_add_u32_e32 v149, v149, v5
	v_add_u32_e32 v149, 0x4800, v149
	v_mul_u32_u24_e32 v4, 0x48, v144
	v_lshlrev_b32_e32 v148, 3, v3
	s_sub_i32 s2, s0, s2
	s_mul_i32 s3, s3, s92
	v_lshlrev_b32_e32 v200, 1, v2
	v_and_b32_e32 v1, 63, v0
	v_add_lshl_u32 v198, v148, v4, 1
	s_add_i32 s2, s2, s3
	s_lshl_b32 s3, s4, 5
	v_lshl_add_u64 v[4:5], s[6:7], 0, v[200:201]
	s_mov_b64 s[4:5], 0x27800000
	v_lshl_add_u64 v[150:151], v[4:5], 0, s[4:5]
	v_lshlrev_b32_e32 v4, 2, v1
	v_and_b32_e32 v0, 7, v0
	v_xor_b32_e32 v209, 0x80, v4
	v_cmp_gt_u32_e64 s[4:5], 32, v1
	v_lshlrev_b32_e32 v1, 4, v3
	v_lshlrev_b32_e32 v4, 12, v3
	v_lshlrev_b32_e32 v200, 4, v0
	v_mul_u32_u24_e32 v199, 0x110, v144
	v_lshl_add_u32 v219, v144, 2, s10
	v_add_u32_e32 v222, s10, v1
	v_add_u32_e32 v5, 0, v148
	v_or_b32_e32 v6, 0x400, v4
	v_or_b32_e32 v8, 0x800, v4
	v_or_b32_e32 v10, 0xc00, v4
	v_or_b32_e32 v12, 0x2000, v4
	v_or_b32_e32 v14, 0x2400, v4
	v_or_b32_e32 v16, 0x2800, v4
	v_or_b32_e32 v18, 0x2c00, v4
	v_or_b32_e32 v20, 0x4000, v4
	v_or_b32_e32 v22, 0x4400, v4
	v_or_b32_e32 v24, 0x4800, v4
	v_or_b32_e32 v26, 0x4c00, v4
	v_or_b32_e32 v28, 0x6000, v4
	v_or_b32_e32 v30, 0x6400, v4
	v_or_b32_e32 v32, 0x6800, v4
	v_or_b32_e32 v34, 0x6c00, v4
	v_lshl_add_u64 v[0:1], s[6:7], 0, v[200:201]
	s_mov_b64 s[10:11], 0x13940400
	s_ashr_i32 s14, s3, 31
	v_ashrrev_i32_e32 v147, 31, v146
	v_lshl_add_u64 v[152:153], v[0:1], 0, s[10:11]
	s_mov_b32 s15, 0
	v_lshl_add_u32 v223, v148, 1, v199
	v_lshlrev_b32_e32 v200, 1, v144
	v_lshlrev_b32_e32 v154, 1, v4
	v_lshlrev_b32_e32 v156, 1, v6
	v_lshlrev_b32_e32 v158, 1, v8
	v_lshlrev_b32_e32 v160, 1, v10
	v_lshlrev_b32_e32 v162, 1, v12
	v_lshlrev_b32_e32 v164, 1, v14
	v_lshlrev_b32_e32 v166, 1, v16
	v_lshlrev_b32_e32 v168, 1, v18
	v_lshlrev_b32_e32 v170, 1, v20
	v_lshlrev_b32_e32 v172, 1, v22
	v_lshlrev_b32_e32 v174, 1, v24
	v_lshlrev_b32_e32 v176, 1, v26
	v_lshlrev_b32_e32 v178, 1, v28
	v_lshlrev_b32_e32 v180, 1, v30
	v_lshlrev_b32_e32 v182, 1, v32
	v_lshlrev_b32_e32 v184, 1, v34
	v_lshlrev_b32_e32 v186, 1, v148
	v_lshlrev_b32_e32 v188, 1, v2
	v_add_u32_e32 v237, v186, v199
	v_add_u32_e32 v238, 0x8c00, v149
	s_branch .LBB0_728

; __device__ __forceinline__ void phase_attn(const Params& p, int S, int lgS, int B, int* counter, LAS unsigned char* lds) {
;     ...
;         for (int t = 0; t < NT; ++t) {
;             const LAS unsigned char* kb = lds + (t & 1) * BUFB; const LAS unsigned char* vb = kb + KB;
;             if (t + 1 < NT) { const bf16_t* kn = ksrc + (size_t)(t + 1) * 128 * 2048; const bf16_t* vn_ = vsrc + (t + 1) * 128;
;                 kreg0 = *(const u32x4*)kn; kreg1 = *(const u32x4*)(kn + (size_t)64 * 2048); vreg0 = *(const u32x4*)vn_; vreg1 = *(const u32x4*)(vn_ + 64); }
;             f32x16 pp[4] = {negm, negm, negm, negm};
;             const LAS unsigned char* kl = kb + klane; const LAS unsigned char* vl = vb + vlane;
; #pragma unroll
;             for (int d0 = 0; d0 < 4; ++d0)
; #pragma unroll
;                 for (int j = 0; j < 4; ++j) { const bf16x8 a = *(const LAS bf16x8*)(kl + (32 * j * 72 + 16 * d0) * 2); pp[j] = __builtin_amdgcn_mfma_f32_32x32x16_bf16(a, qr[d0], pp[j], 0, 0, 0); }
;             float mxa = fmaxf(pp[0][0], pp[1][0]), mxb = fmaxf(pp[2][0], pp[3][0]);
; #pragma unroll
;             for (int r = 1; r < 16; ++r) { mxa = fmaxf(fmaxf(mxa, pp[0][r]), pp[1][r]); mxb = fmaxf(fmaxf(mxb, pp[2][r]), pp[3][r]); }
;             float mx = fmaxf(mxa, mxb);
;             mx = fmaxf(mx, shx(mx, 32, lane));
;             const bool first = (t == 0);
;             if (first || __any(mx > 8.f)) {
;                 const float d = first ? mx : fmaxf(mx, 0.f);
;                 m_run += d;
; #pragma unroll
;                 for (int j = 0; j < 4; ++j)
; #pragma unroll
;                     for (int r = 0; r < 16; ++r) pp[j][r] -= d;
; #pragma unroll
;                 for (int r = 0; r < 16; ++r) negm[r] = -m_run;
;                 if (!first) {
;                     const float alpha = __builtin_amdgcn_exp2f(-d); l_run *= alpha;
;                     if (hi == 0) wsf[r32] = alpha;
;                     LDS_WAIT();
; #pragma unroll
;                     for (int r = 0; r < 16; ++r) { const float f = wsf[crow(r, hi)]; o0[r] *= f; o1[r] *= f; }
;                     LDS_WAIT();
;                 }
;             }
;             float ls = 0.f;
; #pragma unroll
;             for (int j = 0; j < 4; ++j)
; #pragma unroll
;                 for (int r = 0; r < 16; ++r) { pp[j][r] = __builtin_amdgcn_exp2f(pp[j][r]); ls += pp[j][r]; }
;             l_run += ls;
.LBB0_731:
	s_bitcmp1_b32 s18, 0
	s_cselect_b32 s18, 0x8c00, 0
	s_add_i32 s18, s18, 0
	s_cmp_lg_u32 s18, 0
	s_cbranch_scc1 .Latt_fast_odd
	ds_read_b128 v[224:227], v198
	ds_read_b128 v[228:231], v198 offset:4608
	ds_read_b128 v[232:235], v198 offset:9216
	ds_read_b128 v[242:245], v198 offset:13824
	s_mov_b32 s19, 0x43800000
	s_waitcnt lgkmcnt(3)
	v_mfma_f32_32x32x16_bf16 v[96:111], v[224:227], v[112:115], v[32:47]
	ds_read_b128 v[224:227], v198 offset:32
	s_waitcnt lgkmcnt(3)
	v_mfma_f32_32x32x16_bf16 v[80:95], v[228:231], v[112:115], v[32:47]
	ds_read_b128 v[228:231], v198 offset:4640
	s_waitcnt lgkmcnt(3)
	v_mfma_f32_32x32x16_bf16 v[64:79], v[232:235], v[112:115], v[32:47]
	ds_read_b128 v[232:235], v198 offset:9248
	s_waitcnt lgkmcnt(3)
	v_mfma_f32_32x32x16_bf16 v[48:63], v[242:245], v[112:115], v[32:47]
	ds_read_b128 v[242:245], v198 offset:13856
	s_waitcnt lgkmcnt(3)
	v_mfma_f32_32x32x16_bf16 v[96:111], v[224:227], v[116:119], v[96:111]
	ds_read_b128 v[224:227], v198 offset:64
	s_waitcnt lgkmcnt(3)
	v_mfma_f32_32x32x16_bf16 v[80:95], v[228:231], v[116:119], v[80:95]
	ds_read_b128 v[228:231], v198 offset:4672
	s_waitcnt lgkmcnt(3)
	v_mfma_f32_32x32x16_bf16 v[64:79], v[232:235], v[116:119], v[64:79]
	ds_read_b128 v[232:235], v198 offset:9280
	s_waitcnt lgkmcnt(3)
	v_mfma_f32_32x32x16_bf16 v[48:63], v[242:245], v[116:119], v[48:63]
	ds_read_b128 v[242:245], v198 offset:13888
	s_waitcnt lgkmcnt(3)
	v_mfma_f32_32x32x16_bf16 v[96:111], v[224:227], v[120:123], v[96:111]
	ds_read_b128 v[224:227], v198 offset:96
	s_waitcnt lgkmcnt(3)
	v_mfma_f32_32x32x16_bf16 v[80:95], v[228:231], v[120:123], v[80:95]
	ds_read_b128 v[228:231], v198 offset:4704
	s_waitcnt lgkmcnt(3)
	v_mfma_f32_32x32x16_bf16 v[64:79], v[232:235], v[120:123], v[64:79]
	ds_read_b128 v[232:235], v198 offset:9312
	s_waitcnt lgkmcnt(3)
	v_mfma_f32_32x32x16_bf16 v[48:63], v[242:245], v[120:123], v[48:63]
	ds_read_b128 v[242:245], v198 offset:13920
	s_waitcnt lgkmcnt(3)
	v_mfma_f32_32x32x16_bf16 v[96:111], v[224:227], v[124:127], v[96:111]
	s_waitcnt lgkmcnt(2)
	v_mfma_f32_32x32x16_bf16 v[80:95], v[228:231], v[124:127], v[80:95]
	s_waitcnt lgkmcnt(1)
	v_mfma_f32_32x32x16_bf16 v[64:79], v[232:235], v[124:127], v[64:79]
	s_waitcnt lgkmcnt(0)
	v_mfma_f32_32x32x16_bf16 v[48:63], v[242:245], v[124:127], v[48:63]
	ds_read_b128 v[228:231], v237 offset:18432
	ds_read_b128 v[232:235], v237 offset:27136
	ds_read_b128 v[242:245], v237 offset:18464
	s_nop 3
	v_exp_f32_e32 v96, v96
	v_exp_f32_e32 v97, v97
	v_exp_f32_e32 v98, v98
	v_exp_f32_e32 v99, v99
	v_exp_f32_e32 v100, v100
	v_exp_f32_e32 v101, v101
	v_exp_f32_e32 v102, v102
	v_exp_f32_e32 v103, v103
	v_exp_f32_e32 v104, v104
	v_exp_f32_e32 v105, v105
	v_exp_f32_e32 v106, v106
	v_exp_f32_e32 v107, v107
	v_exp_f32_e32 v108, v108
	v_exp_f32_e32 v109, v109
	v_exp_f32_e32 v110, v110
	v_exp_f32_e32 v111, v111
	v_exp_f32_e32 v80, v80
	v_exp_f32_e32 v81, v81
	v_exp_f32_e32 v82, v82
	v_exp_f32_e32 v83, v83
	v_exp_f32_e32 v84, v84
	v_exp_f32_e32 v85, v85
	v_exp_f32_e32 v86, v86
	v_exp_f32_e32 v87, v87
	v_exp_f32_e32 v88, v88
	v_exp_f32_e32 v89, v89
	v_exp_f32_e32 v90, v90
	v_exp_f32_e32 v91, v91
	v_exp_f32_e32 v92, v92
	v_exp_f32_e32 v93, v93
	v_exp_f32_e32 v94, v94
	v_exp_f32_e32 v95, v95
	v_exp_f32_e32 v64, v64
	v_exp_f32_e32 v65, v65
	v_exp_f32_e32 v66, v66
	v_exp_f32_e32 v67, v67
	v_exp_f32_e32 v68, v68
	v_exp_f32_e32 v69, v69
	v_exp_f32_e32 v70, v70
	v_exp_f32_e32 v71, v71
	v_exp_f32_e32 v72, v72
	v_exp_f32_e32 v73, v73
	v_exp_f32_e32 v74, v74
	v_exp_f32_e32 v75, v75
	v_exp_f32_e32 v76, v76
	v_exp_f32_e32 v77, v77
	v_exp_f32_e32 v78, v78
	v_exp_f32_e32 v79, v79
	v_exp_f32_e32 v48, v48
	v_exp_f32_e32 v49, v49
	v_exp_f32_e32 v50, v50
	v_exp_f32_e32 v51, v51
	v_exp_f32_e32 v52, v52
	v_exp_f32_e32 v53, v53
	v_exp_f32_e32 v54, v54
	v_exp_f32_e32 v55, v55
	v_exp_f32_e32 v56, v56
	v_exp_f32_e32 v57, v57
	v_exp_f32_e32 v58, v58
	v_exp_f32_e32 v59, v59
	v_exp_f32_e32 v60, v60
	v_exp_f32_e32 v61, v61
	v_exp_f32_e32 v62, v62
	v_exp_f32_e32 v63, v63
	v_add_f32_e32 v236, v97, v96
	v_add_f32_e32 v236, v98, v236
	v_add_f32_e32 v236, v99, v236
	v_add_f32_e32 v236, v100, v236
	v_add_f32_e32 v236, v101, v236
	v_add_f32_e32 v236, v102, v236
	v_add_f32_e32 v236, v103, v236
	v_add_f32_e32 v236, v104, v236
	v_add_f32_e32 v236, v105, v236
	v_add_f32_e32 v236, v106, v236
	v_add_f32_e32 v236, v107, v236
	v_add_f32_e32 v236, v108, v236
	v_add_f32_e32 v236, v109, v236
	v_add_f32_e32 v236, v110, v236
	v_add_f32_e32 v236, v111, v236
	v_add_f32_e32 v236, v80, v236
	v_add_f32_e32 v236, v81, v236
	v_add_f32_e32 v236, v82, v236
	v_add_f32_e32 v236, v83, v236
	v_add_f32_e32 v236, v84, v236
	v_add_f32_e32 v236, v85, v236
	v_add_f32_e32 v236, v86, v236
	v_add_f32_e32 v236, v87, v236
	v_add_f32_e32 v236, v88, v236
	v_add_f32_e32 v236, v89, v236
	v_add_f32_e32 v236, v90, v236
	v_add_f32_e32 v236, v91, v236
	v_add_f32_e32 v236, v92, v236
	v_add_f32_e32 v236, v93, v236
	v_add_f32_e32 v236, v94, v236
	v_add_f32_e32 v236, v95, v236
	v_add_f32_e32 v236, v64, v236
	v_add_f32_e32 v236, v65, v236
	v_add_f32_e32 v236, v66, v236
	v_add_f32_e32 v236, v67, v236
	v_add_f32_e32 v236, v68, v236
	v_add_f32_e32 v236, v69, v236
	v_add_f32_e32 v236, v70, v236
	v_add_f32_e32 v236, v71, v236
	v_add_f32_e32 v236, v72, v236
	v_add_f32_e32 v236, v73, v236
	v_add_f32_e32 v236, v74, v236
	v_add_f32_e32 v236, v75, v236
	v_add_f32_e32 v236, v76, v236
	v_add_f32_e32 v236, v77, v236
	v_add_f32_e32 v236, v78, v236
	v_add_f32_e32 v236, v79, v236
	v_add_f32_e32 v236, v48, v236
	v_add_f32_e32 v236, v49, v236
	v_add_f32_e32 v236, v50, v236
	v_add_f32_e32 v236, v51, v236
	v_add_f32_e32 v236, v52, v236
	v_add_f32_e32 v236, v53, v236
	v_add_f32_e32 v236, v54, v236
	v_add_f32_e32 v236, v55, v236
	v_add_f32_e32 v236, v56, v236
	v_add_f32_e32 v236, v57, v236
	v_add_f32_e32 v236, v58, v236
	v_add_f32_e32 v236, v59, v236
	v_add_f32_e32 v236, v60, v236
	v_add_f32_e32 v236, v61, v236
	v_add_f32_e32 v236, v62, v236
	v_add_f32_e32 v236, v63, v236
	v_cmp_lt_f32_e32 vcc, s19, v236
	s_cbranch_vccnz .Latt_slow
; #define LAS __attribute__((address_space(3)))
; __device__ __forceinline__ void phase_attn(const Params& p, int S, int lgS, int B, int* counter, LAS unsigned char* lds) {
;     ...
; #pragma unroll
;             for (int j = 0; j < 4; ++j)
; #pragma unroll
;                 for (int kk = 0; kk < 2; ++kk) {
;                     const int ks = 2 * j + kk;
;                     const bf16x8 pa = pack8(pp[j][8 * kk], pp[j][8 * kk + 1], pp[j][8 * kk + 2], pp[j][8 * kk + 3], pp[j][8 * kk + 4], pp[j][8 * kk + 5], pp[j][8 * kk + 6], pp[j][8 * kk + 7]);
;                     const u32x2 v0a = *(const LAS u32x2*)(vl + (16 * ks) * 2), v0b = *(const LAS u32x2*)(vl + (16 * ks + 8) * 2);
;                     const u32x2 v1a = *(const LAS u32x2*)(vl + (32 * 136 + 16 * ks) * 2), v1b = *(const LAS u32x2*)(vl + (32 * 136 + 16 * ks + 8) * 2);
;                     const u32x4 f0 = {v0a.x, v0a.y, v0b.x, v0b.y}, f1 = {v1a.x, v1a.y, v1b.x, v1b.y};
;                     o0 = __builtin_amdgcn_mfma_f32_32x32x16_bf16(pa, __builtin_bit_cast(bf16x8, f0), o0, 0, 0, 0);
;                     o1 = __builtin_amdgcn_mfma_f32_32x32x16_bf16(pa, __builtin_bit_cast(bf16x8, f1), o1, 0, 0, 0);
;                 }
;             if (t + 1 < NT) { LAS unsigned char* nb = lds + ((t + 1) & 1) * BUFB;
;                 *(LAS u32x4*)(nb + kdst) = kreg0; *(LAS u32x4*)(nb + kdst + 64 * 144) = kreg1; *(LAS u32x4*)(nb + vdst) = vreg0; *(LAS u32x4*)(nb + vdst + 128) = vreg1; }
	v_cvt_pk_bf16_f32 v224, v96, v97
	v_cvt_pk_bf16_f32 v225, v98, v99
	v_cvt_pk_bf16_f32 v226, v100, v101
	v_cvt_pk_bf16_f32 v227, v102, v103
	v_add_f32_e32 v195, v195, v236
	s_waitcnt lgkmcnt(1)
	v_mfma_f32_32x32x16_bf16 v[0:15], v[224:227], v[228:231], v[0:15]
	ds_read_b128 v[228:231], v237 offset:27168
	v_mfma_f32_32x32x16_bf16 v[16:31], v[224:227], v[232:235], v[16:31]
	v_cvt_pk_bf16_f32 v224, v104, v105
	v_cvt_pk_bf16_f32 v225, v106, v107
	v_cvt_pk_bf16_f32 v226, v108, v109
	v_cvt_pk_bf16_f32 v227, v110, v111
	ds_read_b128 v[232:235], v237 offset:18496
	s_waitcnt lgkmcnt(1)
	v_mfma_f32_32x32x16_bf16 v[0:15], v[224:227], v[242:245], v[0:15]
	ds_read_b128 v[242:245], v237 offset:27200
	v_mfma_f32_32x32x16_bf16 v[16:31], v[224:227], v[228:231], v[16:31]
	v_cvt_pk_bf16_f32 v224, v80, v81
	v_cvt_pk_bf16_f32 v225, v82, v83
	v_cvt_pk_bf16_f32 v226, v84, v85
	v_cvt_pk_bf16_f32 v227, v86, v87
	ds_read_b128 v[228:231], v237 offset:18528
	s_waitcnt lgkmcnt(1)
	v_mfma_f32_32x32x16_bf16 v[0:15], v[224:227], v[232:235], v[0:15]
	ds_read_b128 v[232:235], v237 offset:27232
	v_mfma_f32_32x32x16_bf16 v[16:31], v[224:227], v[242:245], v[16:31]
	v_cvt_pk_bf16_f32 v224, v88, v89
	v_cvt_pk_bf16_f32 v225, v90, v91
	v_cvt_pk_bf16_f32 v226, v92, v93
	v_cvt_pk_bf16_f32 v227, v94, v95
	ds_read_b128 v[242:245], v237 offset:18560
	s_waitcnt lgkmcnt(1)
	v_mfma_f32_32x32x16_bf16 v[0:15], v[224:227], v[228:231], v[0:15]
	ds_read_b128 v[228:231], v237 offset:27264
	v_mfma_f32_32x32x16_bf16 v[16:31], v[224:227], v[232:235], v[16:31]
	v_cvt_pk_bf16_f32 v224, v64, v65
	v_cvt_pk_bf16_f32 v225, v66, v67
	v_cvt_pk_bf16_f32 v226, v68, v69
	v_cvt_pk_bf16_f32 v227, v70, v71
	ds_read_b128 v[232:235], v237 offset:18592
	s_waitcnt lgkmcnt(1)
	v_mfma_f32_32x32x16_bf16 v[0:15], v[224:227], v[242:245], v[0:15]
	ds_read_b128 v[242:245], v237 offset:27296
	v_mfma_f32_32x32x16_bf16 v[16:31], v[224:227], v[228:231], v[16:31]
	v_cvt_pk_bf16_f32 v224, v72, v73
	v_cvt_pk_bf16_f32 v225, v74, v75
	v_cvt_pk_bf16_f32 v226, v76, v77
	v_cvt_pk_bf16_f32 v227, v78, v79
	ds_read_b128 v[228:231], v237 offset:18624
	s_waitcnt lgkmcnt(1)
	v_mfma_f32_32x32x16_bf16 v[0:15], v[224:227], v[232:235], v[0:15]
	ds_read_b128 v[232:235], v237 offset:27328
	v_mfma_f32_32x32x16_bf16 v[16:31], v[224:227], v[242:245], v[16:31]
	v_cvt_pk_bf16_f32 v224, v48, v49
	v_cvt_pk_bf16_f32 v225, v50, v51
	v_cvt_pk_bf16_f32 v226, v52, v53
	v_cvt_pk_bf16_f32 v227, v54, v55
	ds_read_b128 v[242:245], v237 offset:18656
	s_waitcnt lgkmcnt(1)
	v_mfma_f32_32x32x16_bf16 v[0:15], v[224:227], v[228:231], v[0:15]
	ds_read_b128 v[228:231], v237 offset:27360
	v_mfma_f32_32x32x16_bf16 v[16:31], v[224:227], v[232:235], v[16:31]
	v_cvt_pk_bf16_f32 v224, v56, v57
	v_cvt_pk_bf16_f32 v225, v58, v59
	v_cvt_pk_bf16_f32 v226, v60, v61
	v_cvt_pk_bf16_f32 v227, v62, v63
	s_andn2_b64 vcc, exec, s[26:27]
	s_waitcnt lgkmcnt(0)
	v_mfma_f32_32x32x16_bf16 v[0:15], v[224:227], v[242:245], v[0:15]
	v_mfma_f32_32x32x16_bf16 v[16:31], v[224:227], v[228:231], v[16:31]
	s_cbranch_vccnz .Latt_fast_nowr_e
	s_waitcnt vmcnt(3)
	ds_write_b128 v145, v[128:131] offset:35840
	s_waitcnt vmcnt(2)
	ds_write_b128 v145, v[132:135] offset:45056
	s_waitcnt vmcnt(1)
	ds_write2_b64 v238, v[136:137], v[138:139] offset1:2
	s_waitcnt vmcnt(0)
	ds_write2_b64 v238, v[140:141], v[142:143] offset0:16 offset1:18

; __device__ __forceinline__ void phase_attn(const Params& p, int S, int lgS, int B, int* counter, LAS unsigned char* lds) {
;     ...
;         for (int t = 0; t < NT; ++t) {
;             const LAS unsigned char* kb = lds + (t & 1) * BUFB; const LAS unsigned char* vb = kb + KB;
;             if (t + 1 < NT) { const bf16_t* kn = ksrc + (size_t)(t + 1) * 128 * 2048; const bf16_t* vn_ = vsrc + (t + 1) * 128;
;                 kreg0 = *(const u32x4*)kn; kreg1 = *(const u32x4*)(kn + (size_t)64 * 2048); vreg0 = *(const u32x4*)vn_; vreg1 = *(const u32x4*)(vn_ + 64); }
;             f32x16 pp[4] = {negm, negm, negm, negm};
;             const LAS unsigned char* kl = kb + klane; const LAS unsigned char* vl = vb + vlane;
; #pragma unroll
;             for (int d0 = 0; d0 < 4; ++d0)
; #pragma unroll
;                 for (int j = 0; j < 4; ++j) { const bf16x8 a = *(const LAS bf16x8*)(kl + (32 * j * 72 + 16 * d0) * 2); pp[j] = __builtin_amdgcn_mfma_f32_32x32x16_bf16(a, qr[d0], pp[j], 0, 0, 0); }
;             float mxa = fmaxf(pp[0][0], pp[1][0]), mxb = fmaxf(pp[2][0], pp[3][0]);
; #pragma unroll
;             for (int r = 1; r < 16; ++r) { mxa = fmaxf(fmaxf(mxa, pp[0][r]), pp[1][r]); mxb = fmaxf(fmaxf(mxb, pp[2][r]), pp[3][r]); }
;             float mx = fmaxf(mxa, mxb);
;             mx = fmaxf(mx, shx(mx, 32, lane));
;             const bool first = (t == 0);
;             if (first || __any(mx > 8.f)) {
;                 const float d = first ? mx : fmaxf(mx, 0.f);
;                 m_run += d;
; #pragma unroll
;                 for (int j = 0; j < 4; ++j)
; #pragma unroll
;                     for (int r = 0; r < 16; ++r) pp[j][r] -= d;
; #pragma unroll
;                 for (int r = 0; r < 16; ++r) negm[r] = -m_run;
;                 if (!first) {
;                     const float alpha = __builtin_amdgcn_exp2f(-d); l_run *= alpha;
;                     if (hi == 0) wsf[r32] = alpha;
;                     LDS_WAIT();
; #pragma unroll
;                     for (int r = 0; r < 16; ++r) { const float f = wsf[crow(r, hi)]; o0[r] *= f; o1[r] *= f; }
;                     LDS_WAIT();
;                 }
;             }
;             float ls = 0.f;
; #pragma unroll
;             for (int j = 0; j < 4; ++j)
; #pragma unroll
;                 for (int r = 0; r < 16; ++r) { pp[j][r] = __builtin_amdgcn_exp2f(pp[j][r]); ls += pp[j][r]; }
;             l_run += ls;
.Latt_fast_odd:
	ds_read_b128 v[224:227], v198 offset:35840
	ds_read_b128 v[228:231], v198 offset:40448
	ds_read_b128 v[232:235], v198 offset:45056
	ds_read_b128 v[242:245], v198 offset:49664
	s_mov_b32 s19, 0x43800000
	s_waitcnt lgkmcnt(3)
	v_mfma_f32_32x32x16_bf16 v[96:111], v[224:227], v[112:115], v[32:47]
	ds_read_b128 v[224:227], v198 offset:35872
	s_waitcnt lgkmcnt(3)
	v_mfma_f32_32x32x16_bf16 v[80:95], v[228:231], v[112:115], v[32:47]
	ds_read_b128 v[228:231], v198 offset:40480
	s_waitcnt lgkmcnt(3)
	v_mfma_f32_32x32x16_bf16 v[64:79], v[232:235], v[112:115], v[32:47]
	ds_read_b128 v[232:235], v198 offset:45088
	s_waitcnt lgkmcnt(3)
	v_mfma_f32_32x32x16_bf16 v[48:63], v[242:245], v[112:115], v[32:47]
	ds_read_b128 v[242:245], v198 offset:49696
	s_waitcnt lgkmcnt(3)
	v_mfma_f32_32x32x16_bf16 v[96:111], v[224:227], v[116:119], v[96:111]
	ds_read_b128 v[224:227], v198 offset:35904
	s_waitcnt lgkmcnt(3)
	v_mfma_f32_32x32x16_bf16 v[80:95], v[228:231], v[116:119], v[80:95]
	ds_read_b128 v[228:231], v198 offset:40512
	s_waitcnt lgkmcnt(3)
	v_mfma_f32_32x32x16_bf16 v[64:79], v[232:235], v[116:119], v[64:79]
	ds_read_b128 v[232:235], v198 offset:45120
	s_waitcnt lgkmcnt(3)
	v_mfma_f32_32x32x16_bf16 v[48:63], v[242:245], v[116:119], v[48:63]
	ds_read_b128 v[242:245], v198 offset:49728
	s_waitcnt lgkmcnt(3)
	v_mfma_f32_32x32x16_bf16 v[96:111], v[224:227], v[120:123], v[96:111]
	ds_read_b128 v[224:227], v198 offset:35936
	s_waitcnt lgkmcnt(3)
	v_mfma_f32_32x32x16_bf16 v[80:95], v[228:231], v[120:123], v[80:95]
	ds_read_b128 v[228:231], v198 offset:40544
	s_waitcnt lgkmcnt(3)
	v_mfma_f32_32x32x16_bf16 v[64:79], v[232:235], v[120:123], v[64:79]
	ds_read_b128 v[232:235], v198 offset:45152
	s_waitcnt lgkmcnt(3)
	v_mfma_f32_32x32x16_bf16 v[48:63], v[242:245], v[120:123], v[48:63]
	ds_read_b128 v[242:245], v198 offset:49760
	s_waitcnt lgkmcnt(3)
	v_mfma_f32_32x32x16_bf16 v[96:111], v[224:227], v[124:127], v[96:111]
	s_waitcnt lgkmcnt(2)
	v_mfma_f32_32x32x16_bf16 v[80:95], v[228:231], v[124:127], v[80:95]
	s_waitcnt lgkmcnt(1)
	v_mfma_f32_32x32x16_bf16 v[64:79], v[232:235], v[124:127], v[64:79]
	s_waitcnt lgkmcnt(0)
	v_mfma_f32_32x32x16_bf16 v[48:63], v[242:245], v[124:127], v[48:63]
	ds_read_b128 v[228:231], v237 offset:54272
	ds_read_b128 v[232:235], v237 offset:62976
	ds_read_b128 v[242:245], v237 offset:54304
	s_nop 3
	v_exp_f32_e32 v96, v96
	v_exp_f32_e32 v97, v97
	v_exp_f32_e32 v98, v98
	v_exp_f32_e32 v99, v99
	v_exp_f32_e32 v100, v100
	v_exp_f32_e32 v101, v101
	v_exp_f32_e32 v102, v102
	v_exp_f32_e32 v103, v103
	v_exp_f32_e32 v104, v104
	v_exp_f32_e32 v105, v105
	v_exp_f32_e32 v106, v106
	v_exp_f32_e32 v107, v107
	v_exp_f32_e32 v108, v108
	v_exp_f32_e32 v109, v109
	v_exp_f32_e32 v110, v110
	v_exp_f32_e32 v111, v111
	v_exp_f32_e32 v80, v80
	v_exp_f32_e32 v81, v81
	v_exp_f32_e32 v82, v82
	v_exp_f32_e32 v83, v83
	v_exp_f32_e32 v84, v84
	v_exp_f32_e32 v85, v85
	v_exp_f32_e32 v86, v86
	v_exp_f32_e32 v87, v87
	v_exp_f32_e32 v88, v88
	v_exp_f32_e32 v89, v89
	v_exp_f32_e32 v90, v90
	v_exp_f32_e32 v91, v91
	v_exp_f32_e32 v92, v92
	v_exp_f32_e32 v93, v93
	v_exp_f32_e32 v94, v94
	v_exp_f32_e32 v95, v95
	v_exp_f32_e32 v64, v64
	v_exp_f32_e32 v65, v65
	v_exp_f32_e32 v66, v66
	v_exp_f32_e32 v67, v67
	v_exp_f32_e32 v68, v68
	v_exp_f32_e32 v69, v69
	v_exp_f32_e32 v70, v70
	v_exp_f32_e32 v71, v71
	v_exp_f32_e32 v72, v72
	v_exp_f32_e32 v73, v73
	v_exp_f32_e32 v74, v74
	v_exp_f32_e32 v75, v75
	v_exp_f32_e32 v76, v76
	v_exp_f32_e32 v77, v77
	v_exp_f32_e32 v78, v78
	v_exp_f32_e32 v79, v79
	v_exp_f32_e32 v48, v48
	v_exp_f32_e32 v49, v49
	v_exp_f32_e32 v50, v50
	v_exp_f32_e32 v51, v51
	v_exp_f32_e32 v52, v52
	v_exp_f32_e32 v53, v53
	v_exp_f32_e32 v54, v54
	v_exp_f32_e32 v55, v55
	v_exp_f32_e32 v56, v56
	v_exp_f32_e32 v57, v57
	v_exp_f32_e32 v58, v58
	v_exp_f32_e32 v59, v59
	v_exp_f32_e32 v60, v60
	v_exp_f32_e32 v61, v61
	v_exp_f32_e32 v62, v62
	v_exp_f32_e32 v63, v63
	v_add_f32_e32 v236, v97, v96
	v_add_f32_e32 v236, v98, v236
	v_add_f32_e32 v236, v99, v236
	v_add_f32_e32 v236, v100, v236
	v_add_f32_e32 v236, v101, v236
	v_add_f32_e32 v236, v102, v236
	v_add_f32_e32 v236, v103, v236
	v_add_f32_e32 v236, v104, v236
	v_add_f32_e32 v236, v105, v236
	v_add_f32_e32 v236, v106, v236
	v_add_f32_e32 v236, v107, v236
	v_add_f32_e32 v236, v108, v236
	v_add_f32_e32 v236, v109, v236
	v_add_f32_e32 v236, v110, v236
	v_add_f32_e32 v236, v111, v236
	v_add_f32_e32 v236, v80, v236
	v_add_f32_e32 v236, v81, v236
	v_add_f32_e32 v236, v82, v236
	v_add_f32_e32 v236, v83, v236
	v_add_f32_e32 v236, v84, v236
	v_add_f32_e32 v236, v85, v236
	v_add_f32_e32 v236, v86, v236
	v_add_f32_e32 v236, v87, v236
	v_add_f32_e32 v236, v88, v236
	v_add_f32_e32 v236, v89, v236
	v_add_f32_e32 v236, v90, v236
	v_add_f32_e32 v236, v91, v236
	v_add_f32_e32 v236, v92, v236
	v_add_f32_e32 v236, v93, v236
	v_add_f32_e32 v236, v94, v236
	v_add_f32_e32 v236, v95, v236
	v_add_f32_e32 v236, v64, v236
	v_add_f32_e32 v236, v65, v236
	v_add_f32_e32 v236, v66, v236
	v_add_f32_e32 v236, v67, v236
	v_add_f32_e32 v236, v68, v236
	v_add_f32_e32 v236, v69, v236
	v_add_f32_e32 v236, v70, v236
	v_add_f32_e32 v236, v71, v236
	v_add_f32_e32 v236, v72, v236
	v_add_f32_e32 v236, v73, v236
	v_add_f32_e32 v236, v74, v236
	v_add_f32_e32 v236, v75, v236
	v_add_f32_e32 v236, v76, v236
	v_add_f32_e32 v236, v77, v236
	v_add_f32_e32 v236, v78, v236
	v_add_f32_e32 v236, v79, v236
	v_add_f32_e32 v236, v48, v236
	v_add_f32_e32 v236, v49, v236
	v_add_f32_e32 v236, v50, v236
	v_add_f32_e32 v236, v51, v236
	v_add_f32_e32 v236, v52, v236
	v_add_f32_e32 v236, v53, v236
	v_add_f32_e32 v236, v54, v236
	v_add_f32_e32 v236, v55, v236
	v_add_f32_e32 v236, v56, v236
	v_add_f32_e32 v236, v57, v236
	v_add_f32_e32 v236, v58, v236
	v_add_f32_e32 v236, v59, v236
	v_add_f32_e32 v236, v60, v236
	v_add_f32_e32 v236, v61, v236
	v_add_f32_e32 v236, v62, v236
	v_add_f32_e32 v236, v63, v236
	v_cmp_lt_f32_e32 vcc, s19, v236
	s_cbranch_vccnz .Latt_slow
; #define LAS __attribute__((address_space(3)))
; __device__ __forceinline__ void phase_attn(const Params& p, int S, int lgS, int B, int* counter, LAS unsigned char* lds) {
;     ...
;             l_run += ls;
; #pragma unroll
;             for (int j = 0; j < 4; ++j)
; #pragma unroll
;                 for (int kk = 0; kk < 2; ++kk) {
;                     const int ks = 2 * j + kk;
;                     const bf16x8 pa = pack8(pp[j][8 * kk], pp[j][8 * kk + 1], pp[j][8 * kk + 2], pp[j][8 * kk + 3], pp[j][8 * kk + 4], pp[j][8 * kk + 5], pp[j][8 * kk + 6], pp[j][8 * kk + 7]);
;                     const u32x2 v0a = *(const LAS u32x2*)(vl + (16 * ks) * 2), v0b = *(const LAS u32x2*)(vl + (16 * ks + 8) * 2);
;                     const u32x2 v1a = *(const LAS u32x2*)(vl + (32 * 136 + 16 * ks) * 2), v1b = *(const LAS u32x2*)(vl + (32 * 136 + 16 * ks + 8) * 2);
;                     const u32x4 f0 = {v0a.x, v0a.y, v0b.x, v0b.y}, f1 = {v1a.x, v1a.y, v1b.x, v1b.y};
;                     o0 = __builtin_amdgcn_mfma_f32_32x32x16_bf16(pa, __builtin_bit_cast(bf16x8, f0), o0, 0, 0, 0);
;                     o1 = __builtin_amdgcn_mfma_f32_32x32x16_bf16(pa, __builtin_bit_cast(bf16x8, f1), o1, 0, 0, 0);
;                 }
;             if (t + 1 < NT) { LAS unsigned char* nb = lds + ((t + 1) & 1) * BUFB;
;                 *(LAS u32x4*)(nb + kdst) = kreg0; *(LAS u32x4*)(nb + kdst + 64 * 144) = kreg1; *(LAS u32x4*)(nb + vdst) = vreg0; *(LAS u32x4*)(nb + vdst + 128) = vreg1; }
	v_cvt_pk_bf16_f32 v224, v96, v97
	v_cvt_pk_bf16_f32 v225, v98, v99
	v_cvt_pk_bf16_f32 v226, v100, v101
	v_cvt_pk_bf16_f32 v227, v102, v103
	v_add_f32_e32 v195, v195, v236
	s_waitcnt lgkmcnt(1)
	v_mfma_f32_32x32x16_bf16 v[0:15], v[224:227], v[228:231], v[0:15]
	ds_read_b128 v[228:231], v237 offset:63008
	v_mfma_f32_32x32x16_bf16 v[16:31], v[224:227], v[232:235], v[16:31]
	v_cvt_pk_bf16_f32 v224, v104, v105
	v_cvt_pk_bf16_f32 v225, v106, v107
	v_cvt_pk_bf16_f32 v226, v108, v109
	v_cvt_pk_bf16_f32 v227, v110, v111
	ds_read_b128 v[232:235], v237 offset:54336
	s_waitcnt lgkmcnt(1)
	v_mfma_f32_32x32x16_bf16 v[0:15], v[224:227], v[242:245], v[0:15]
	ds_read_b128 v[242:245], v237 offset:63040
	v_mfma_f32_32x32x16_bf16 v[16:31], v[224:227], v[228:231], v[16:31]
	v_cvt_pk_bf16_f32 v224, v80, v81
	v_cvt_pk_bf16_f32 v225, v82, v83
	v_cvt_pk_bf16_f32 v226, v84, v85
	v_cvt_pk_bf16_f32 v227, v86, v87
	ds_read_b128 v[228:231], v237 offset:54368
	s_waitcnt lgkmcnt(1)
	v_mfma_f32_32x32x16_bf16 v[0:15], v[224:227], v[232:235], v[0:15]
	ds_read_b128 v[232:235], v237 offset:63072
	v_mfma_f32_32x32x16_bf16 v[16:31], v[224:227], v[242:245], v[16:31]
	v_cvt_pk_bf16_f32 v224, v88, v89
	v_cvt_pk_bf16_f32 v225, v90, v91
	v_cvt_pk_bf16_f32 v226, v92, v93
	v_cvt_pk_bf16_f32 v227, v94, v95
	ds_read_b128 v[242:245], v237 offset:54400
	s_waitcnt lgkmcnt(1)
	v_mfma_f32_32x32x16_bf16 v[0:15], v[224:227], v[228:231], v[0:15]
	ds_read_b128 v[228:231], v237 offset:63104
	v_mfma_f32_32x32x16_bf16 v[16:31], v[224:227], v[232:235], v[16:31]
	v_cvt_pk_bf16_f32 v224, v64, v65
	v_cvt_pk_bf16_f32 v225, v66, v67
	v_cvt_pk_bf16_f32 v226, v68, v69
	v_cvt_pk_bf16_f32 v227, v70, v71
	ds_read_b128 v[232:235], v237 offset:54432
	s_waitcnt lgkmcnt(1)
	v_mfma_f32_32x32x16_bf16 v[0:15], v[224:227], v[242:245], v[0:15]
	ds_read_b128 v[242:245], v237 offset:63136
	v_mfma_f32_32x32x16_bf16 v[16:31], v[224:227], v[228:231], v[16:31]
	v_cvt_pk_bf16_f32 v224, v72, v73
	v_cvt_pk_bf16_f32 v225, v74, v75
	v_cvt_pk_bf16_f32 v226, v76, v77
	v_cvt_pk_bf16_f32 v227, v78, v79
	ds_read_b128 v[228:231], v237 offset:54464
	s_waitcnt lgkmcnt(1)
	v_mfma_f32_32x32x16_bf16 v[0:15], v[224:227], v[232:235], v[0:15]
	ds_read_b128 v[232:235], v237 offset:63168
	v_mfma_f32_32x32x16_bf16 v[16:31], v[224:227], v[242:245], v[16:31]
	v_cvt_pk_bf16_f32 v224, v48, v49
	v_cvt_pk_bf16_f32 v225, v50, v51
	v_cvt_pk_bf16_f32 v226, v52, v53
	v_cvt_pk_bf16_f32 v227, v54, v55
	ds_read_b128 v[242:245], v237 offset:54496
	s_waitcnt lgkmcnt(1)
	v_mfma_f32_32x32x16_bf16 v[0:15], v[224:227], v[228:231], v[0:15]
	ds_read_b128 v[228:231], v237 offset:63200
	v_mfma_f32_32x32x16_bf16 v[16:31], v[224:227], v[232:235], v[16:31]
	v_cvt_pk_bf16_f32 v224, v56, v57
	v_cvt_pk_bf16_f32 v225, v58, v59
	v_cvt_pk_bf16_f32 v226, v60, v61
	v_cvt_pk_bf16_f32 v227, v62, v63
	s_andn2_b64 vcc, exec, s[26:27]
	s_waitcnt lgkmcnt(0)
	v_mfma_f32_32x32x16_bf16 v[0:15], v[224:227], v[242:245], v[0:15]
	v_mfma_f32_32x32x16_bf16 v[16:31], v[224:227], v[228:231], v[16:31]
	s_cbranch_vccnz .Latt_fast_nowr_o
	s_waitcnt vmcnt(3)
	ds_write_b128 v145, v[128:131]
	s_waitcnt vmcnt(2)
	ds_write_b128 v145, v[132:135] offset:9216
	s_waitcnt vmcnt(1)
	ds_write2_b64 v149, v[136:137], v[138:139] offset1:2
	s_waitcnt vmcnt(0)
	ds_write2_b64 v149, v[140:141], v[142:143] offset0:16 offset1:18
